# SSD chunk loops: the 10 per-chunk conv tap/bias loads issued before the chunk-top barrier (same VM op order, raw-row wait vmcnt(15)), hiding their L2 latency behind the barrier
# speedup vs baseline: 1.0109x; 1.0109x over previous
.LBB0_760:
	s_and_b32 s51, s18, 1
	s_lshl_b32 s4, s51, 9
	s_add_i32 s5, s77, s4
	s_add_i32 s4, s5, s50
	s_andn2_b64 vcc, exec, s[12:13]
	s_cbranch_vccnz .Lcw_skip_p
	v_mov_b32_e32 v2, v104
	v_ashrrev_i32_e32 v3, 31, v2
	v_lshlrev_b64 v[2:3], 2, v[2:3]
	v_lshl_add_u64 v[76:77], s[42:43], 0, v[2:3]
	v_add_co_u32_e32 v70, vcc, 0x1000, v76
	global_load_dwordx4 v[64:67], v[76:77], off offset:16
	global_load_dwordx4 v[80:83], v[76:77], off
	v_addc_co_u32_e32 v71, vcc, 0, v77, vcc
	v_add_co_u32_e32 v74, vcc, s25, v76
	v_lshl_add_u64 v[68:69], v[76:77], 0, s[90:91]
	s_nop 0
	v_addc_co_u32_e32 v75, vcc, 0, v77, vcc
	v_lshl_add_u64 v[72:73], v[76:77], 0, s[92:93]
	v_lshl_add_u64 v[78:79], v[76:77], 0, s[94:95]
	v_add_co_u32_e32 v76, vcc, s2, v76
	v_lshl_add_u64 v[2:3], s[22:23], 0, v[2:3]
	s_nop 0
	v_addc_co_u32_e32 v77, vcc, 0, v77, vcc
	global_load_dwordx4 v[84:87], v[70:71], off offset:1024
	s_nop 0
	global_load_dwordx4 v[68:71], v[68:69], off offset:16
	s_nop 0
	global_load_dwordx4 v[88:91], v[74:75], off offset:2048
	s_nop 0
	global_load_dwordx4 v[72:75], v[72:73], off offset:16
	s_nop 0
	global_load_dwordx4 v[92:95], v[76:77], off offset:3072
	s_nop 0
	global_load_dwordx4 v[76:79], v[78:79], off offset:16
	s_nop 0
	global_load_dwordx4 v[96:99], v[2:3], off offset:16
	global_load_dwordx4 v[100:103], v[2:3], off
.Lcw_skip_p:
	s_waitcnt lgkmcnt(0)
	s_barrier
	v_mov_b32_e32 v1, s4
	ds_read_b32 v218, v1 offset:64768
	v_cndmask_b32_e64 v1, 0, 1, s[12:13]
	v_cmp_ne_u32_e64 s[10:11], 1, v1
	s_andn2_b64 vcc, exec, s[12:13]
	s_cbranch_vccnz .LBB0_817
	s_waitcnt vmcnt(15)
	v_lshlrev_b32_e32 v118, 16, v4
	v_lshlrev_b32_e32 v2, 16, v8
	v_and_b32_e32 v3, 0xffff0000, v8
	v_and_b32_e32 v119, 0xffff0000, v4
	s_waitcnt vmcnt(14)
	v_lshlrev_b32_e32 v126, 16, v12
	v_and_b32_e32 v127, 0xffff0000, v12
	s_waitcnt vmcnt(16)
	v_lshlrev_b32_e32 v134, 16, v16
	v_and_b32_e32 v135, 0xffff0000, v16
	v_lshlrev_b32_e32 v120, 16, v5
	v_and_b32_e32 v121, 0xffff0000, v5
	v_lshlrev_b32_e32 v128, 16, v13
	v_and_b32_e32 v129, 0xffff0000, v13
	v_lshlrev_b32_e32 v136, 16, v17
	v_and_b32_e32 v137, 0xffff0000, v17
	v_lshlrev_b32_e32 v122, 16, v6
	v_and_b32_e32 v123, 0xffff0000, v6
	v_lshlrev_b32_e32 v130, 16, v14
	v_and_b32_e32 v131, 0xffff0000, v14
	v_lshlrev_b32_e32 v138, 16, v18
	v_and_b32_e32 v139, 0xffff0000, v18
	v_lshlrev_b32_e32 v114, 16, v11
	v_and_b32_e32 v125, 0xffff0000, v11
	v_and_b32_e32 v124, 0xffff0000, v7
	v_lshlrev_b32_e32 v133, 16, v7
	v_and_b32_e32 v141, 0xffff0000, v15
	v_and_b32_e32 v140, 0xffff0000, v19
	v_lshlrev_b32_e32 v132, 16, v15
	v_lshlrev_b32_e32 v1, 16, v19
	s_mov_b64 s[48:49], -1
	s_cmp_gt_i32 s76, 1
	s_waitcnt vmcnt(9)
	v_mov_b32_e32 v115, v67
	s_waitcnt vmcnt(6)
	v_mul_f32_e32 v142, v70, v133
	s_waitcnt vmcnt(4)
	v_mov_b32_e32 v117, v75
	s_waitcnt vmcnt(2)
	v_mov_b32_e32 v116, v79
	s_waitcnt vmcnt(0)
	v_pk_fma_f32 v[2:3], v[80:81], v[2:3], v[100:101]
	v_pk_mul_f32 v[150:151], v[116:117], v[140:141]
	v_pk_fma_f32 v[2:3], v[84:85], v[118:119], v[2:3]
	v_mul_f32_e32 v144, v74, v132
	v_pk_fma_f32 v[2:3], v[88:89], v[126:127], v[2:3]
	v_mov_b32_e32 v145, v151
	v_pk_fma_f32 v[2:3], v[92:93], v[134:135], v[2:3]
	v_mul_f32_e32 v146, v78, v1
	v_mul_f32_e32 v108, 0xbfb8aa3b, v2
	v_mul_f32_e32 v109, 0xbfb8aa3b, v3
	v_exp_f32_e32 v108, v108
	v_exp_f32_e32 v109, v109
	v_mov_b32_e32 v147, v150
	v_add_f32_e32 v108, 1.0, v108
	v_add_f32_e32 v109, 1.0, v109
	v_rcp_f32_e32 v108, v108
	v_rcp_f32_e32 v109, v109
	s_nop 0
	v_pk_mul_f32 v[2:3], v[2:3], v[108:109]
	v_lshlrev_b32_e32 v108, 16, v9
	v_and_b32_e32 v109, 0xffff0000, v9
	v_pk_fma_f32 v[108:109], v[82:83], v[108:109], v[102:103]
	s_nop 0
	v_pk_fma_f32 v[108:109], v[86:87], v[120:121], v[108:109]
	s_nop 0
	v_pk_fma_f32 v[108:109], v[90:91], v[128:129], v[108:109]
	s_nop 0
	v_pk_fma_f32 v[108:109], v[94:95], v[136:137], v[108:109]
	s_nop 0
	v_mul_f32_e32 v110, 0xbfb8aa3b, v108
	v_mul_f32_e32 v111, 0xbfb8aa3b, v109
	v_exp_f32_e32 v110, v110
	v_exp_f32_e32 v111, v111
	v_add_f32_e32 v110, 1.0, v110
	v_add_f32_e32 v111, 1.0, v111
	v_rcp_f32_e32 v110, v110
	v_rcp_f32_e32 v111, v111
	s_nop 0
	v_pk_mul_f32 v[108:109], v[108:109], v[110:111]
	v_lshlrev_b32_e32 v110, 16, v10
	v_and_b32_e32 v111, 0xffff0000, v10
	v_pk_fma_f32 v[110:111], v[64:65], v[110:111], v[96:97]
	s_nop 0
	v_pk_fma_f32 v[110:111], v[68:69], v[122:123], v[110:111]
	s_nop 0
	v_pk_fma_f32 v[110:111], v[72:73], v[130:131], v[110:111]
	s_nop 0
	v_pk_fma_f32 v[110:111], v[76:77], v[138:139], v[110:111]
	s_nop 0
	v_mul_f32_e32 v112, 0xbfb8aa3b, v110
	v_mul_f32_e32 v113, 0xbfb8aa3b, v111
	v_exp_f32_e32 v112, v112
	v_exp_f32_e32 v113, v113
	v_add_f32_e32 v112, 1.0, v112
	v_add_f32_e32 v113, 1.0, v113
	v_rcp_f32_e32 v112, v112
	v_rcp_f32_e32 v113, v113
	s_nop 0
	v_pk_mul_f32 v[110:111], v[110:111], v[112:113]
	v_mul_f32_e32 v112, v66, v114
	v_mov_b32_e32 v114, v71
	v_pk_mul_f32 v[148:149], v[114:115], v[124:125]
	s_nop 0
	v_mov_b32_e32 v113, v149
	v_pk_add_f32 v[112:113], v[112:113], v[98:99]
	v_mov_b32_e32 v143, v148
	v_pk_add_f32 v[112:113], v[142:143], v[112:113]
	s_nop 0
	v_pk_add_f32 v[112:113], v[144:145], v[112:113]
	s_nop 0
	v_pk_add_f32 v[112:113], v[146:147], v[112:113]
	s_nop 0
	v_mul_f32_e32 v67, 0xbfb8aa3b, v112
	v_exp_f32_e32 v67, v67
	s_nop 0
	v_add_f32_e32 v67, 1.0, v67
	v_rcp_f32_e32 v142, v67
	v_mul_f32_e32 v67, 0xbfb8aa3b, v113
	v_exp_f32_e32 v67, v67
	s_nop 0
	v_add_f32_e32 v67, 1.0, v67
	v_rcp_f32_e32 v143, v67
	s_nop 0
	v_pk_mul_f32 v[112:113], v[112:113], v[142:143]
	s_cbranch_scc0 .LBB0_763
	v_cvt_pk_bf16_f32 v142, v2, v3
	v_cvt_pk_bf16_f32 v143, v108, v109
	v_cvt_pk_bf16_f32 v144, v110, v111
	v_cvt_pk_bf16_f32 v145, v112, v113
	v_add_u32_e32 v67, s77, v207
	ds_write_b128 v67, v[142:145]
	s_mov_b64 s[48:49], 0

.LBB0_939:
	s_and_b32 s52, s4, 1
	s_lshl_b32 s5, s52, 9
	s_add_i32 s5, s51, s5
	s_add_i32 s10, s5, s41
	s_andn2_b64 vcc, exec, s[12:13]
	s_cbranch_vccnz .Lcw_skip_s
	v_mov_b32_e32 v2, v104
	v_ashrrev_i32_e32 v3, 31, v2
	v_lshlrev_b64 v[2:3], 2, v[2:3]
	v_lshl_add_u64 v[76:77], s[34:35], 0, v[2:3]
	v_add_co_u32_e32 v70, vcc, 0x1000, v76
	global_load_dwordx4 v[64:67], v[76:77], off offset:16
	global_load_dwordx4 v[80:83], v[76:77], off
	v_addc_co_u32_e32 v71, vcc, 0, v77, vcc
	v_add_co_u32_e32 v74, vcc, s25, v76
	v_lshl_add_u64 v[68:69], v[76:77], 0, s[90:91]
	s_nop 0
	v_addc_co_u32_e32 v75, vcc, 0, v77, vcc
	v_lshl_add_u64 v[72:73], v[76:77], 0, s[92:93]
	v_lshl_add_u64 v[78:79], v[76:77], 0, s[94:95]
	v_add_co_u32_e32 v76, vcc, s2, v76
	v_lshl_add_u64 v[2:3], s[16:17], 0, v[2:3]
	s_nop 0
	v_addc_co_u32_e32 v77, vcc, 0, v77, vcc
	global_load_dwordx4 v[84:87], v[70:71], off offset:1024
	s_nop 0
	global_load_dwordx4 v[68:71], v[68:69], off offset:16
	s_nop 0
	global_load_dwordx4 v[88:91], v[74:75], off offset:2048
	s_nop 0
	global_load_dwordx4 v[72:75], v[72:73], off offset:16
	s_nop 0
	global_load_dwordx4 v[92:95], v[76:77], off offset:3072
	s_nop 0
	global_load_dwordx4 v[76:79], v[78:79], off offset:16
	s_nop 0
	global_load_dwordx4 v[96:99], v[2:3], off offset:16
	global_load_dwordx4 v[100:103], v[2:3], off
.Lcw_skip_s:
	s_waitcnt lgkmcnt(0)
	s_barrier
	v_mov_b32_e32 v1, s10
	ds_read_b32 v218, v1 offset:64768
	v_cndmask_b32_e64 v1, 0, 1, s[12:13]
	v_cmp_ne_u32_e64 s[10:11], 1, v1
	s_andn2_b64 vcc, exec, s[12:13]
	s_cbranch_vccnz .LBB0_996
	s_waitcnt vmcnt(15)
	v_lshlrev_b32_e32 v118, 16, v20
	v_lshlrev_b32_e32 v2, 16, v24
	v_and_b32_e32 v3, 0xffff0000, v24
	v_and_b32_e32 v119, 0xffff0000, v20
	s_waitcnt vmcnt(14)
	v_lshlrev_b32_e32 v126, 16, v28
	v_and_b32_e32 v127, 0xffff0000, v28
	s_waitcnt vmcnt(16)
	v_lshlrev_b32_e32 v134, 16, v32
	v_and_b32_e32 v135, 0xffff0000, v32
	v_lshlrev_b32_e32 v120, 16, v21
	v_and_b32_e32 v121, 0xffff0000, v21
	v_lshlrev_b32_e32 v128, 16, v29
	v_and_b32_e32 v129, 0xffff0000, v29
	v_lshlrev_b32_e32 v136, 16, v33
	v_and_b32_e32 v137, 0xffff0000, v33
	v_lshlrev_b32_e32 v122, 16, v22
	v_and_b32_e32 v123, 0xffff0000, v22
	v_lshlrev_b32_e32 v130, 16, v30
	v_and_b32_e32 v131, 0xffff0000, v30
	v_lshlrev_b32_e32 v138, 16, v34
	v_and_b32_e32 v139, 0xffff0000, v34
	v_lshlrev_b32_e32 v114, 16, v27
	v_and_b32_e32 v125, 0xffff0000, v27
	v_and_b32_e32 v124, 0xffff0000, v23
	v_lshlrev_b32_e32 v133, 16, v23
	v_and_b32_e32 v141, 0xffff0000, v31
	v_and_b32_e32 v140, 0xffff0000, v35
	v_lshlrev_b32_e32 v132, 16, v31
	v_lshlrev_b32_e32 v1, 16, v35
	s_mov_b64 s[38:39], -1
	s_cmp_gt_i32 s48, 1
	s_waitcnt vmcnt(9)
	v_mov_b32_e32 v115, v67
	s_waitcnt vmcnt(6)
	v_mul_f32_e32 v142, v70, v133
	s_waitcnt vmcnt(4)
	v_mov_b32_e32 v117, v75
	s_waitcnt vmcnt(2)
	v_mov_b32_e32 v116, v79
	s_waitcnt vmcnt(0)
	v_pk_fma_f32 v[2:3], v[80:81], v[2:3], v[100:101]
	v_pk_mul_f32 v[150:151], v[116:117], v[140:141]
	v_pk_fma_f32 v[2:3], v[84:85], v[118:119], v[2:3]
	v_mul_f32_e32 v144, v74, v132
	v_pk_fma_f32 v[2:3], v[88:89], v[126:127], v[2:3]
	v_mov_b32_e32 v145, v151
	v_pk_fma_f32 v[2:3], v[92:93], v[134:135], v[2:3]
	v_mul_f32_e32 v146, v78, v1
	v_mul_f32_e32 v108, 0xbfb8aa3b, v2
	v_mul_f32_e32 v109, 0xbfb8aa3b, v3
	v_exp_f32_e32 v108, v108
	v_exp_f32_e32 v109, v109
	v_mov_b32_e32 v147, v150
	v_add_f32_e32 v108, 1.0, v108
	v_add_f32_e32 v109, 1.0, v109
	v_rcp_f32_e32 v108, v108
	v_rcp_f32_e32 v109, v109
	s_nop 0
	v_pk_mul_f32 v[2:3], v[2:3], v[108:109]
	v_lshlrev_b32_e32 v108, 16, v25
	v_and_b32_e32 v109, 0xffff0000, v25
	v_pk_fma_f32 v[108:109], v[82:83], v[108:109], v[102:103]
	s_nop 0
	v_pk_fma_f32 v[108:109], v[86:87], v[120:121], v[108:109]
	s_nop 0
	v_pk_fma_f32 v[108:109], v[90:91], v[128:129], v[108:109]
	s_nop 0
	v_pk_fma_f32 v[108:109], v[94:95], v[136:137], v[108:109]
	s_nop 0
	v_mul_f32_e32 v110, 0xbfb8aa3b, v108
	v_mul_f32_e32 v111, 0xbfb8aa3b, v109
	v_exp_f32_e32 v110, v110
	v_exp_f32_e32 v111, v111
	v_add_f32_e32 v110, 1.0, v110
	v_add_f32_e32 v111, 1.0, v111
	v_rcp_f32_e32 v110, v110
	v_rcp_f32_e32 v111, v111
	s_nop 0
	v_pk_mul_f32 v[108:109], v[108:109], v[110:111]
	v_lshlrev_b32_e32 v110, 16, v26
	v_and_b32_e32 v111, 0xffff0000, v26
	v_pk_fma_f32 v[110:111], v[64:65], v[110:111], v[96:97]
	s_nop 0
	v_pk_fma_f32 v[110:111], v[68:69], v[122:123], v[110:111]
	s_nop 0
	v_pk_fma_f32 v[110:111], v[72:73], v[130:131], v[110:111]
	s_nop 0
	v_pk_fma_f32 v[110:111], v[76:77], v[138:139], v[110:111]
	s_nop 0
	v_mul_f32_e32 v112, 0xbfb8aa3b, v110
	v_mul_f32_e32 v113, 0xbfb8aa3b, v111
	v_exp_f32_e32 v112, v112
	v_exp_f32_e32 v113, v113
	v_add_f32_e32 v112, 1.0, v112
	v_add_f32_e32 v113, 1.0, v113
	v_rcp_f32_e32 v112, v112
	v_rcp_f32_e32 v113, v113
	s_nop 0
	v_pk_mul_f32 v[110:111], v[110:111], v[112:113]
	v_mul_f32_e32 v112, v66, v114
	v_mov_b32_e32 v114, v71
	v_pk_mul_f32 v[148:149], v[114:115], v[124:125]
	s_nop 0
	v_mov_b32_e32 v113, v149
	v_pk_add_f32 v[112:113], v[112:113], v[98:99]
	v_mov_b32_e32 v143, v148
	v_pk_add_f32 v[112:113], v[142:143], v[112:113]
	s_nop 0
	v_pk_add_f32 v[112:113], v[144:145], v[112:113]
	s_nop 0
	v_pk_add_f32 v[112:113], v[146:147], v[112:113]
	s_nop 0
	v_mul_f32_e32 v67, 0xbfb8aa3b, v112
	v_exp_f32_e32 v67, v67
	s_nop 0
	v_add_f32_e32 v67, 1.0, v67
	v_rcp_f32_e32 v142, v67
	v_mul_f32_e32 v67, 0xbfb8aa3b, v113
	v_exp_f32_e32 v67, v67
	s_nop 0
	v_add_f32_e32 v67, 1.0, v67
	v_rcp_f32_e32 v143, v67
	s_nop 0
	v_pk_mul_f32 v[112:113], v[112:113], v[142:143]
	s_cbranch_scc0 .LBB0_942
	v_cvt_pk_bf16_f32 v142, v2, v3
	v_cvt_pk_bf16_f32 v143, v108, v109
	v_cvt_pk_bf16_f32 v144, v110, v111
	v_cvt_pk_bf16_f32 v145, v112, v113
	v_add_u32_e32 v67, s51, v208
	ds_write_b128 v67, v[142:145]
	s_mov_b64 s[38:39], 0
